# MLP up/down GEMM: first K-loop iteration peeled with C=0 in the first MFMA of each accumulator; the per-unit 128 v_mov accumulator zeroing removed
# speedup vs baseline: 1.0115x; 1.0088x over previous
; #define G8_STAGE(bufoff, gbase, voff) do { const char* _gb = uptr((const char*)(gbase)); _Pragma("unroll") for (int _i = 0; _i < 2; ++_i) \
;         __builtin_amdgcn_global_load_lds((const unsigned*)(_gb + (voff)[_i]), (LAS unsigned*)(lds + (bufoff) + ldsw + _i * 8192), 16, 0, 0); } while (0)
; #define G8_LDA(dst, b, h) do { _Pragma("unroll") for (int m = 0; m < 4; ++m) _Pragma("unroll") for (int k = 0; k < 2; ++k) dst[m][k] = *(const LAS bf16x8*)(lds + G8_SA(b, h) + aoff + m * 2048 + k * 1024); } while (0)
; #define G8_LDB(dst, b, h) do { _Pragma("unroll") for (int n = 0; n < 2; ++n) _Pragma("unroll") for (int k = 0; k < 2; ++k) dst[n][k] = *(const LAS bf16x8*)(lds + G8_SB(b, h) + boff + n * 2048 + k * 1024); } while (0)
; #define G8_MMA(ai, bj, At, Bt_) do { __builtin_amdgcn_s_setprio(1); _Pragma("unroll") for (int m = 0; m < 4; ++m) _Pragma("unroll") for (int n = 0; n < 2; ++n) _Pragma("unroll") for (int k = 0; k < 2; ++k) \
;         acc[ai][bj][m][n] = __builtin_amdgcn_mfma_f32_16x16x32_bf16(Bt_[n][k], At[m][k], acc[ai][bj][m][n], 0, 0, 0); __builtin_amdgcn_s_setprio(0); } while (0)
; #define G8_WAIT_L(n) asm volatile("s_waitcnt lgkmcnt(" #n ")" ::: "memory")
; #define G8_BAR __builtin_amdgcn_s_barrier()
;     ...
;         const bool has_next = next_unit<NKH, ROT>(ui + 1, nM, nN, nxt);
;         const char* nA = uptr(has_next ? (const char*)A + (size_t)nxt.pm * tstepA + (size_t)nxt.kh * kchunk + E.a_off(nxt.pn) : cA);
;         const char* nB = uptr(has_next ? (const char*)Bt + (size_t)nxt.pn * tstepB + (size_t)nxt.kh * kchunk : cB);
;         for (int t = 0; t < nt; t += 2) {
;             const bool last = (t == nt - 2);
;             const char* a1 = cA + (size_t)(t + 1) * kstep;
;             const char* a2 = last ? nA : cA + (size_t)(t + 2) * kstep; const char* b2 = last ? nB : cB + (size_t)(t + 2) * kstep;
;             const char* a3 = a2 + kstep; const char* b3 = b2 + kstep;
;             G8_LDB(B0, 0, 0); G8_SCHED; G8_LDA(At, 0, 0); G8_STAGE(G8_SA(1, 1), a1 + hstepA, voffA);
;             G8_WAIT_L(8); G8_BAR; G8_WAIT_L(0); G8_MMA(0, 0, At, B0); G8_BAR; G8_SCHED;
;             G8_LDB(B1, 0, 1); G8_STAGE(G8_SB(0, 0), b2, voffB);
;             G8_BAR; G8_WAIT_L(0); G8_MMA(0, 1, At, B1); G8_BAR;
;             G8_LDA(At, 0, 1); G8_STAGE(G8_SA(0, 0), a2, voffA);
;             G8_BAR; G8_WAIT_L(0); G8_MMA(1, 0, At, B0); G8_BAR; G8_SCHED;
.LBB0_1091:
	s_ashr_i32 s11, s10, 31
	v_cmp_lt_u64_e32 vcc, s[14:15], v[136:137]
	s_lshl_b64 s[14:15], s[10:11], 19
	s_add_u32 s11, s8, s14
	s_addc_u32 s13, s9, s15
	s_and_b64 s[14:15], vcc, exec
	s_cselect_b32 s14, s11, s18
	s_cselect_b32 s15, s13, s19
	s_ashr_i32 s13, s12, 31
	s_lshl_b64 s[16:17], s[12:13], 19
	s_add_u32 s11, s25, s16
	s_addc_u32 s13, s26, s17
	s_and_b64 s[16:17], vcc, exec
	s_cselect_b32 s16, s11, s2
	s_cselect_b32 s17, s13, s3
	s_add_u32 s11, s2, 0x100
	s_addc_u32 s13, s3, 0
	s_add_u32 s2, s18, 0x40080
	s_addc_u32 s3, s19, 0
	s_mov_b32 s41, -2
	ds_read_b128 v[144:147], v150
	ds_read_b128 v[154:157], v150 offset:1024
	ds_read_b128 v[158:161], v150 offset:2048
	ds_read_b128 v[162:165], v150 offset:3072
	s_add_u32 s18, s2, 0xfffc0080
	s_addc_u32 s19, s3, -1
	s_cmp_eq_u32 s41, 12
	s_cselect_b32 s22, s14, s18
	s_cselect_b32 s23, s15, s19
	s_cselect_b32 s18, s16, s11
	s_cselect_b32 s19, s17, s13
	s_add_u32 s20, s22, 0x80
	s_addc_u32 s21, s23, 0
	v_lshl_add_u64 v[140:141], s[2:3], 0, v[134:135]
	s_add_i32 m0, s28, 0xc000
	ds_read_b128 v[166:169], v151
	ds_read_b128 v[170:173], v151 offset:1024
	ds_read_b128 v[174:177], v151 offset:2048
	ds_read_b128 v[178:181], v151 offset:3072
	ds_read_b128 v[182:185], v151 offset:4096
	ds_read_b128 v[186:189], v151 offset:5120
	ds_read_b128 v[190:193], v151 offset:6144
	ds_read_b128 v[194:197], v151 offset:7168
	global_load_lds_dwordx4 v[140:141], off
	v_lshl_add_u64 v[140:141], s[2:3], 0, v[132:133]
	s_add_i32 m0, s28, 0xe000
	s_nop 0
	global_load_lds_dwordx4 v[140:141], off
	s_waitcnt lgkmcnt(8)
	s_barrier
	s_waitcnt lgkmcnt(0)
	s_setprio 1
	s_waitcnt lgkmcnt(0)
	v_mfma_f32_16x16x32_bf16 v[124:127], v[144:147], v[166:169], 0
	v_mfma_f32_16x16x32_bf16 v[120:123], v[158:161], v[166:169], 0
	v_mfma_f32_16x16x32_bf16 v[108:111], v[144:147], v[174:177], 0
	v_mfma_f32_16x16x32_bf16 v[104:107], v[158:161], v[174:177], 0
	v_mfma_f32_16x16x32_bf16 v[92:95], v[144:147], v[182:185], 0
	v_mfma_f32_16x16x32_bf16 v[88:91], v[158:161], v[182:185], 0
	v_mfma_f32_16x16x32_bf16 v[76:79], v[144:147], v[190:193], 0
	v_mfma_f32_16x16x32_bf16 v[72:75], v[158:161], v[190:193], 0
	v_mfma_f32_16x16x32_bf16 v[124:127], v[154:157], v[170:173], v[124:127]
	v_mfma_f32_16x16x32_bf16 v[120:123], v[162:165], v[170:173], v[120:123]
	v_mfma_f32_16x16x32_bf16 v[108:111], v[154:157], v[178:181], v[108:111]
	v_mfma_f32_16x16x32_bf16 v[104:107], v[162:165], v[178:181], v[104:107]
	v_mfma_f32_16x16x32_bf16 v[92:95], v[154:157], v[186:189], v[92:95]
	v_mfma_f32_16x16x32_bf16 v[88:91], v[162:165], v[186:189], v[88:91]
	v_mfma_f32_16x16x32_bf16 v[76:79], v[154:157], v[194:197], v[76:79]
	v_mfma_f32_16x16x32_bf16 v[72:75], v[162:165], v[194:197], v[72:75]
	s_setprio 0
	s_barrier
	s_add_i32 s42, s37, s27
	v_lshl_add_u64 v[140:141], s[18:19], 0, v[128:129]
	s_mov_b32 m0, s42
	ds_read_b128 v[198:201], v152
	ds_read_b128 v[202:205], v152 offset:1024
	ds_read_b128 v[206:209], v152 offset:2048
	ds_read_b128 v[210:213], v152 offset:3072
	global_load_lds_dwordx4 v[140:141], off
	v_lshl_add_u64 v[140:141], s[18:19], 0, v[130:131]
	s_add_i32 m0, s42, 0x2000
	s_nop 0
	global_load_lds_dwordx4 v[140:141], off
	s_barrier
	s_waitcnt lgkmcnt(0)
	s_setprio 1
	s_waitcnt lgkmcnt(0)
	v_mfma_f32_16x16x32_bf16 v[116:119], v[198:201], v[166:169], 0
	v_mfma_f32_16x16x32_bf16 v[112:115], v[206:209], v[166:169], 0
	v_mfma_f32_16x16x32_bf16 v[100:103], v[198:201], v[174:177], 0
	v_mfma_f32_16x16x32_bf16 v[96:99], v[206:209], v[174:177], 0
	v_mfma_f32_16x16x32_bf16 v[84:87], v[198:201], v[182:185], 0
	v_mfma_f32_16x16x32_bf16 v[80:83], v[206:209], v[182:185], 0
	v_mfma_f32_16x16x32_bf16 v[68:71], v[198:201], v[190:193], 0
	v_mfma_f32_16x16x32_bf16 v[64:67], v[206:209], v[190:193], 0
	v_mfma_f32_16x16x32_bf16 v[116:119], v[202:205], v[170:173], v[116:119]
	v_mfma_f32_16x16x32_bf16 v[112:115], v[210:213], v[170:173], v[112:115]
	v_mfma_f32_16x16x32_bf16 v[100:103], v[202:205], v[178:181], v[100:103]
	v_mfma_f32_16x16x32_bf16 v[96:99], v[210:213], v[178:181], v[96:99]
	v_mfma_f32_16x16x32_bf16 v[84:87], v[202:205], v[186:189], v[84:87]
	v_mfma_f32_16x16x32_bf16 v[80:83], v[210:213], v[186:189], v[80:83]
	v_mfma_f32_16x16x32_bf16 v[68:71], v[202:205], v[194:197], v[68:71]
	v_mfma_f32_16x16x32_bf16 v[64:67], v[210:213], v[194:197], v[64:67]
	s_setprio 0
	s_mov_b32 m0, s28
	v_lshl_add_u64 v[140:141], s[22:23], 0, v[134:135]
	s_barrier
	ds_read_b128 v[166:169], v151 offset:16384
	ds_read_b128 v[170:173], v151 offset:17408
	ds_read_b128 v[174:177], v151 offset:18432
	ds_read_b128 v[178:181], v151 offset:19456
	ds_read_b128 v[182:185], v151 offset:20480
	ds_read_b128 v[186:189], v151 offset:21504
	ds_read_b128 v[190:193], v151 offset:22528
	ds_read_b128 v[194:197], v151 offset:23552
	global_load_lds_dwordx4 v[140:141], off
	v_lshl_add_u64 v[140:141], s[22:23], 0, v[132:133]
	s_mov_b32 m0, s29
	s_nop 0
	global_load_lds_dwordx4 v[140:141], off
	s_barrier
	s_waitcnt lgkmcnt(0)
	s_setprio 1
	s_waitcnt lgkmcnt(0)
	v_mfma_f32_16x16x32_bf16 v[60:63], v[144:147], v[166:169], 0
	v_mfma_f32_16x16x32_bf16 v[56:59], v[158:161], v[166:169], 0
	v_mfma_f32_16x16x32_bf16 v[44:47], v[144:147], v[174:177], 0
	v_mfma_f32_16x16x32_bf16 v[40:43], v[158:161], v[174:177], 0
	v_mfma_f32_16x16x32_bf16 v[28:31], v[144:147], v[182:185], 0
	v_mfma_f32_16x16x32_bf16 v[24:27], v[158:161], v[182:185], 0
	v_mfma_f32_16x16x32_bf16 v[12:15], v[144:147], v[190:193], 0
	v_mfma_f32_16x16x32_bf16 v[8:11], v[158:161], v[190:193], 0
	v_mfma_f32_16x16x32_bf16 v[60:63], v[154:157], v[170:173], v[60:63]
	v_mfma_f32_16x16x32_bf16 v[56:59], v[162:165], v[170:173], v[56:59]
	v_mfma_f32_16x16x32_bf16 v[44:47], v[154:157], v[178:181], v[44:47]
	v_mfma_f32_16x16x32_bf16 v[40:43], v[162:165], v[178:181], v[40:43]
	v_mfma_f32_16x16x32_bf16 v[28:31], v[154:157], v[186:189], v[28:31]
	v_mfma_f32_16x16x32_bf16 v[24:27], v[162:165], v[186:189], v[24:27]
	v_mfma_f32_16x16x32_bf16 v[12:15], v[154:157], v[194:197], v[12:15]
	v_mfma_f32_16x16x32_bf16 v[8:11], v[162:165], v[194:197], v[8:11]
	s_setprio 0
	s_barrier
; #define G8_STAGE(bufoff, gbase, voff) do { const char* _gb = uptr((const char*)(gbase)); _Pragma("unroll") for (int _i = 0; _i < 2; ++_i) \
;         __builtin_amdgcn_global_load_lds((const unsigned*)(_gb + (voff)[_i]), (LAS unsigned*)(lds + (bufoff) + ldsw + _i * 8192), 16, 0, 0); } while (0)
; #define G8_LDA(dst, b, h) do { _Pragma("unroll") for (int m = 0; m < 4; ++m) _Pragma("unroll") for (int k = 0; k < 2; ++k) dst[m][k] = *(const LAS bf16x8*)(lds + G8_SA(b, h) + aoff + m * 2048 + k * 1024); } while (0)
; #define G8_LDB(dst, b, h) do { _Pragma("unroll") for (int n = 0; n < 2; ++n) _Pragma("unroll") for (int k = 0; k < 2; ++k) dst[n][k] = *(const LAS bf16x8*)(lds + G8_SB(b, h) + boff + n * 2048 + k * 1024); } while (0)
; #define G8_MMA(ai, bj, At, Bt_) do { __builtin_amdgcn_s_setprio(1); _Pragma("unroll") for (int m = 0; m < 4; ++m) _Pragma("unroll") for (int n = 0; n < 2; ++n) _Pragma("unroll") for (int k = 0; k < 2; ++k) \
;         acc[ai][bj][m][n] = __builtin_amdgcn_mfma_f32_16x16x32_bf16(Bt_[n][k], At[m][k], acc[ai][bj][m][n], 0, 0, 0); __builtin_amdgcn_s_setprio(0); } while (0)
; #define G8_WAIT_V(n) asm volatile("s_waitcnt vmcnt(" #n ")" ::: "memory")
; #define G8_WAIT_L(n) asm volatile("s_waitcnt lgkmcnt(" #n ")" ::: "memory")
; #define G8_BAR __builtin_amdgcn_s_barrier()
; #define G8_SCHED __builtin_amdgcn_sched_barrier(0)
;     ...
;             G8_STAGE(G8_SB(0, 1), b2 + hstepB, voffB);
;             G8_WAIT_V(6); G8_BAR; G8_MMA(1, 1, At, B1); G8_BAR;
;             G8_LDB(B0, 1, 0); G8_SCHED; G8_LDA(At, 1, 0); G8_STAGE(G8_SA(0, 1), a2 + hstepA, voffA);
;             G8_WAIT_L(8); G8_BAR; G8_WAIT_L(0); G8_MMA(0, 0, At, B0); G8_BAR; G8_SCHED;
;             G8_LDB(B1, 1, 1); G8_STAGE(G8_SB(1, 0), b3, voffB);
;             G8_BAR; G8_WAIT_L(0); G8_MMA(0, 1, At, B1); G8_BAR;
;             G8_LDA(At, 1, 1); G8_STAGE(G8_SA(1, 0), a3, voffA);
	s_add_u32 s42, s18, 0x40000
	s_addc_u32 s43, s19, 0
	s_add_i32 s44, s38, s27
	v_lshl_add_u64 v[140:141], s[42:43], 0, v[128:129]
	s_mov_b32 m0, s44
	s_nop 0
	global_load_lds_dwordx4 v[140:141], off
	v_lshl_add_u64 v[140:141], s[42:43], 0, v[130:131]
	s_add_i32 m0, s44, 0x2000
	s_nop 0
	global_load_lds_dwordx4 v[140:141], off
	s_waitcnt vmcnt(6)
	s_barrier
	s_setprio 1
	v_mfma_f32_16x16x32_bf16 v[52:55], v[198:201], v[166:169], 0
	v_mfma_f32_16x16x32_bf16 v[48:51], v[206:209], v[166:169], 0
	v_mfma_f32_16x16x32_bf16 v[36:39], v[198:201], v[174:177], 0
	v_mfma_f32_16x16x32_bf16 v[32:35], v[206:209], v[174:177], 0
	v_mfma_f32_16x16x32_bf16 v[20:23], v[198:201], v[182:185], 0
	v_mfma_f32_16x16x32_bf16 v[16:19], v[206:209], v[182:185], 0
	v_mfma_f32_16x16x32_bf16 v[4:7], v[198:201], v[190:193], 0
	v_mfma_f32_16x16x32_bf16 v[0:3], v[206:209], v[190:193], 0
	v_mfma_f32_16x16x32_bf16 v[52:55], v[202:205], v[170:173], v[52:55]
	v_mfma_f32_16x16x32_bf16 v[48:51], v[210:213], v[170:173], v[48:51]
	v_mfma_f32_16x16x32_bf16 v[36:39], v[202:205], v[178:181], v[36:39]
	v_mfma_f32_16x16x32_bf16 v[32:35], v[210:213], v[178:181], v[32:35]
	v_mfma_f32_16x16x32_bf16 v[20:23], v[202:205], v[186:189], v[20:23]
	v_mfma_f32_16x16x32_bf16 v[16:19], v[210:213], v[186:189], v[16:19]
	v_mfma_f32_16x16x32_bf16 v[4:7], v[202:205], v[194:197], v[4:7]
	v_mfma_f32_16x16x32_bf16 v[0:3], v[210:213], v[194:197], v[0:3]
	s_setprio 0
	s_add_i32 s42, 0, 0x18000
	v_add_u32_e32 v140, s42, v149
	s_barrier
	ds_read_b128 v[144:147], v140
	ds_read_b128 v[154:157], v140 offset:1024
	ds_read_b128 v[158:161], v140 offset:2048
	ds_read_b128 v[162:165], v140 offset:3072
	s_add_u32 s22, s22, 0x40000
	s_addc_u32 s23, s23, 0
	s_mov_b32 m0, s30
	v_lshl_add_u64 v[140:141], s[22:23], 0, v[134:135]
	ds_read_b128 v[166:169], v151 offset:32768
	ds_read_b128 v[170:173], v151 offset:33792
	ds_read_b128 v[174:177], v151 offset:34816
	ds_read_b128 v[178:181], v151 offset:35840
	ds_read_b128 v[182:185], v151 offset:36864
	ds_read_b128 v[186:189], v151 offset:37888
	ds_read_b128 v[190:193], v151 offset:38912
	ds_read_b128 v[194:197], v151 offset:39936
	global_load_lds_dwordx4 v[140:141], off
	v_lshl_add_u64 v[140:141], s[22:23], 0, v[132:133]
	s_mov_b32 m0, s31
	s_nop 0
	global_load_lds_dwordx4 v[140:141], off
	s_waitcnt lgkmcnt(8)
	s_barrier
	s_waitcnt lgkmcnt(0)
	s_setprio 1
	s_waitcnt lgkmcnt(0)
	v_mfma_f32_16x16x32_bf16 v[124:127], v[144:147], v[166:169], v[124:127]
	v_mfma_f32_16x16x32_bf16 v[120:123], v[158:161], v[166:169], v[120:123]
	v_mfma_f32_16x16x32_bf16 v[108:111], v[144:147], v[174:177], v[108:111]
	v_mfma_f32_16x16x32_bf16 v[104:107], v[158:161], v[174:177], v[104:107]
	v_mfma_f32_16x16x32_bf16 v[92:95], v[144:147], v[182:185], v[92:95]
	v_mfma_f32_16x16x32_bf16 v[88:91], v[158:161], v[182:185], v[88:91]
	v_mfma_f32_16x16x32_bf16 v[76:79], v[144:147], v[190:193], v[76:79]
	v_mfma_f32_16x16x32_bf16 v[72:75], v[158:161], v[190:193], v[72:75]
	v_mfma_f32_16x16x32_bf16 v[124:127], v[154:157], v[170:173], v[124:127]
	v_mfma_f32_16x16x32_bf16 v[120:123], v[162:165], v[170:173], v[120:123]
	v_mfma_f32_16x16x32_bf16 v[108:111], v[154:157], v[178:181], v[108:111]
	v_mfma_f32_16x16x32_bf16 v[104:107], v[162:165], v[178:181], v[104:107]
	v_mfma_f32_16x16x32_bf16 v[92:95], v[154:157], v[186:189], v[92:95]
	v_mfma_f32_16x16x32_bf16 v[88:91], v[162:165], v[186:189], v[88:91]
	v_mfma_f32_16x16x32_bf16 v[76:79], v[154:157], v[194:197], v[76:79]
	v_mfma_f32_16x16x32_bf16 v[72:75], v[162:165], v[194:197], v[72:75]
	s_setprio 0
	s_barrier
	s_add_i32 s43, 0, 0x1c000
	s_add_u32 s22, s18, 0x80
	v_add_u32_e32 v140, s43, v149
	s_addc_u32 s23, s19, 0
	s_add_i32 s42, s42, s27
	ds_read_b128 v[198:201], v140
	ds_read_b128 v[202:205], v140 offset:1024
	ds_read_b128 v[206:209], v140 offset:2048
	ds_read_b128 v[210:213], v140 offset:3072
	v_lshl_add_u64 v[140:141], s[22:23], 0, v[128:129]
	s_mov_b32 m0, s42
	s_nop 0
	global_load_lds_dwordx4 v[140:141], off
	v_lshl_add_u64 v[140:141], s[22:23], 0, v[130:131]
	s_add_i32 m0, s42, 0x2000
	s_nop 0
	global_load_lds_dwordx4 v[140:141], off
	s_barrier
; #define G8_STAGE(bufoff, gbase, voff) do { const char* _gb = uptr((const char*)(gbase)); _Pragma("unroll") for (int _i = 0; _i < 2; ++_i) \
;         __builtin_amdgcn_global_load_lds((const unsigned*)(_gb + (voff)[_i]), (LAS unsigned*)(lds + (bufoff) + ldsw + _i * 8192), 16, 0, 0); } while (0)
; #define G8_LDA(dst, b, h) do { _Pragma("unroll") for (int m = 0; m < 4; ++m) _Pragma("unroll") for (int k = 0; k < 2; ++k) dst[m][k] = *(const LAS bf16x8*)(lds + G8_SA(b, h) + aoff + m * 2048 + k * 1024); } while (0)
; #define G8_MMA(ai, bj, At, Bt_) do { __builtin_amdgcn_s_setprio(1); _Pragma("unroll") for (int m = 0; m < 4; ++m) _Pragma("unroll") for (int n = 0; n < 2; ++n) _Pragma("unroll") for (int k = 0; k < 2; ++k) \
;         acc[ai][bj][m][n] = __builtin_amdgcn_mfma_f32_16x16x32_bf16(Bt_[n][k], At[m][k], acc[ai][bj][m][n], 0, 0, 0); __builtin_amdgcn_s_setprio(0); } while (0)
; #define G8_WAIT_V(n) asm volatile("s_waitcnt vmcnt(" #n ")" ::: "memory")
; #define G8_WAIT_L(n) asm volatile("s_waitcnt lgkmcnt(" #n ")" ::: "memory")
; #define G8_BAR __builtin_amdgcn_s_barrier()
; #define G8_SCHED __builtin_amdgcn_sched_barrier(0)
;     ...
;             G8_LDA(At, 1, 1); G8_STAGE(G8_SA(1, 0), a3, voffA);
;             G8_BAR; G8_WAIT_L(0); G8_MMA(1, 0, At, B0); G8_BAR; G8_SCHED;
;             G8_STAGE(G8_SB(1, 1), b3 + hstepB, voffB);
;             G8_WAIT_V(6); G8_BAR; G8_MMA(1, 1, At, B1); G8_BAR;
;         }
	s_waitcnt lgkmcnt(0)
	s_setprio 1
	s_waitcnt lgkmcnt(0)
	v_mfma_f32_16x16x32_bf16 v[116:119], v[198:201], v[166:169], v[116:119]
	v_mfma_f32_16x16x32_bf16 v[112:115], v[206:209], v[166:169], v[112:115]
	v_mfma_f32_16x16x32_bf16 v[100:103], v[198:201], v[174:177], v[100:103]
	v_mfma_f32_16x16x32_bf16 v[96:99], v[206:209], v[174:177], v[96:99]
	v_mfma_f32_16x16x32_bf16 v[84:87], v[198:201], v[182:185], v[84:87]
	v_mfma_f32_16x16x32_bf16 v[80:83], v[206:209], v[182:185], v[80:83]
	v_mfma_f32_16x16x32_bf16 v[68:71], v[198:201], v[190:193], v[68:71]
	v_mfma_f32_16x16x32_bf16 v[64:67], v[206:209], v[190:193], v[64:67]
	v_mfma_f32_16x16x32_bf16 v[116:119], v[202:205], v[170:173], v[116:119]
	v_mfma_f32_16x16x32_bf16 v[112:115], v[210:213], v[170:173], v[112:115]
	v_mfma_f32_16x16x32_bf16 v[100:103], v[202:205], v[178:181], v[100:103]
	v_mfma_f32_16x16x32_bf16 v[96:99], v[210:213], v[178:181], v[96:99]
	v_mfma_f32_16x16x32_bf16 v[84:87], v[202:205], v[186:189], v[84:87]
	v_mfma_f32_16x16x32_bf16 v[80:83], v[210:213], v[186:189], v[80:83]
	v_mfma_f32_16x16x32_bf16 v[68:71], v[202:205], v[194:197], v[68:71]
	v_mfma_f32_16x16x32_bf16 v[64:67], v[210:213], v[194:197], v[64:67]
	s_setprio 0
	s_mov_b32 m0, s34
	v_lshl_add_u64 v[140:141], s[20:21], 0, v[134:135]
	s_barrier
	ds_read_b128 v[166:169], v151 offset:49152
	ds_read_b128 v[170:173], v151 offset:50176
	ds_read_b128 v[174:177], v151 offset:51200
	ds_read_b128 v[178:181], v151 offset:52224
	ds_read_b128 v[182:185], v151 offset:53248
	ds_read_b128 v[186:189], v151 offset:54272
	ds_read_b128 v[190:193], v151 offset:55296
	ds_read_b128 v[194:197], v151 offset:56320
	global_load_lds_dwordx4 v[140:141], off
	v_lshl_add_u64 v[140:141], s[20:21], 0, v[132:133]
	s_mov_b32 m0, s35
	s_nop 0
	global_load_lds_dwordx4 v[140:141], off
	s_barrier
	s_waitcnt lgkmcnt(0)
	s_setprio 1
	s_waitcnt lgkmcnt(0)
	v_mfma_f32_16x16x32_bf16 v[60:63], v[144:147], v[166:169], v[60:63]
	v_mfma_f32_16x16x32_bf16 v[56:59], v[158:161], v[166:169], v[56:59]
	v_mfma_f32_16x16x32_bf16 v[44:47], v[144:147], v[174:177], v[44:47]
	v_mfma_f32_16x16x32_bf16 v[40:43], v[158:161], v[174:177], v[40:43]
	v_mfma_f32_16x16x32_bf16 v[28:31], v[144:147], v[182:185], v[28:31]
	v_mfma_f32_16x16x32_bf16 v[24:27], v[158:161], v[182:185], v[24:27]
	v_mfma_f32_16x16x32_bf16 v[12:15], v[144:147], v[190:193], v[12:15]
	v_mfma_f32_16x16x32_bf16 v[8:11], v[158:161], v[190:193], v[8:11]
	v_mfma_f32_16x16x32_bf16 v[60:63], v[154:157], v[170:173], v[60:63]
	v_mfma_f32_16x16x32_bf16 v[56:59], v[162:165], v[170:173], v[56:59]
	v_mfma_f32_16x16x32_bf16 v[44:47], v[154:157], v[178:181], v[44:47]
	v_mfma_f32_16x16x32_bf16 v[40:43], v[162:165], v[178:181], v[40:43]
	v_mfma_f32_16x16x32_bf16 v[28:31], v[154:157], v[186:189], v[28:31]
	v_mfma_f32_16x16x32_bf16 v[24:27], v[162:165], v[186:189], v[24:27]
	v_mfma_f32_16x16x32_bf16 v[12:15], v[154:157], v[194:197], v[12:15]
	v_mfma_f32_16x16x32_bf16 v[8:11], v[162:165], v[194:197], v[8:11]
	s_setprio 0
	s_barrier
	s_add_u32 s18, s18, 0x40080
	s_addc_u32 s19, s19, 0
	s_add_i32 s20, s43, s27
	v_lshl_add_u64 v[140:141], s[18:19], 0, v[128:129]
	s_mov_b32 m0, s20
	s_nop 0
	global_load_lds_dwordx4 v[140:141], off
	v_lshl_add_u64 v[140:141], s[18:19], 0, v[130:131]
	s_add_i32 m0, s20, 0x2000
	s_nop 0
	global_load_lds_dwordx4 v[140:141], off
	s_waitcnt vmcnt(6)
	s_barrier
	s_setprio 1
	v_mfma_f32_16x16x32_bf16 v[52:55], v[198:201], v[166:169], v[52:55]
	v_mfma_f32_16x16x32_bf16 v[48:51], v[206:209], v[166:169], v[48:51]
	v_mfma_f32_16x16x32_bf16 v[36:39], v[198:201], v[174:177], v[36:39]
	v_mfma_f32_16x16x32_bf16 v[32:35], v[206:209], v[174:177], v[32:35]
	v_mfma_f32_16x16x32_bf16 v[20:23], v[198:201], v[182:185], v[20:23]
	v_mfma_f32_16x16x32_bf16 v[16:19], v[206:209], v[182:185], v[16:19]
	v_mfma_f32_16x16x32_bf16 v[4:7], v[198:201], v[190:193], v[4:7]
	v_mfma_f32_16x16x32_bf16 v[0:3], v[206:209], v[190:193], v[0:3]
	v_mfma_f32_16x16x32_bf16 v[52:55], v[202:205], v[170:173], v[52:55]
	v_mfma_f32_16x16x32_bf16 v[48:51], v[210:213], v[170:173], v[48:51]
	v_mfma_f32_16x16x32_bf16 v[36:39], v[202:205], v[178:181], v[36:39]
	v_mfma_f32_16x16x32_bf16 v[32:35], v[210:213], v[178:181], v[32:35]
	v_mfma_f32_16x16x32_bf16 v[20:23], v[202:205], v[186:189], v[20:23]
	v_mfma_f32_16x16x32_bf16 v[16:19], v[210:213], v[186:189], v[16:19]
	v_mfma_f32_16x16x32_bf16 v[4:7], v[202:205], v[194:197], v[4:7]
	v_mfma_f32_16x16x32_bf16 v[0:3], v[210:213], v[194:197], v[0:3]
	s_setprio 0
	s_add_i32 s41, s41, 2
	s_add_u32 s11, s11, 0x100
	s_addc_u32 s13, s13, 0
	s_add_u32 s2, s2, 0x100
	s_addc_u32 s3, s3, 0
	s_cmp_gt_u32 s41, 13
	s_barrier

; #define G8_STAGE(bufoff, gbase, voff) do { const char* _gb = uptr((const char*)(gbase)); _Pragma("unroll") for (int _i = 0; _i < 2; ++_i) \
;         __builtin_amdgcn_global_load_lds((const unsigned*)(_gb + (voff)[_i]), (LAS unsigned*)(lds + (bufoff) + ldsw + _i * 8192), 16, 0, 0); } while (0)
; #define G8_LDA(dst, b, h) do { _Pragma("unroll") for (int m = 0; m < 4; ++m) _Pragma("unroll") for (int k = 0; k < 2; ++k) dst[m][k] = *(const LAS bf16x8*)(lds + G8_SA(b, h) + aoff + m * 2048 + k * 1024); } while (0)
; #define G8_LDB(dst, b, h) do { _Pragma("unroll") for (int n = 0; n < 2; ++n) _Pragma("unroll") for (int k = 0; k < 2; ++k) dst[n][k] = *(const LAS bf16x8*)(lds + G8_SB(b, h) + boff + n * 2048 + k * 1024); } while (0)
; #define G8_MMA(ai, bj, At, Bt_) do { __builtin_amdgcn_s_setprio(1); _Pragma("unroll") for (int m = 0; m < 4; ++m) _Pragma("unroll") for (int n = 0; n < 2; ++n) _Pragma("unroll") for (int k = 0; k < 2; ++k) \
;         acc[ai][bj][m][n] = __builtin_amdgcn_mfma_f32_16x16x32_bf16(Bt_[n][k], At[m][k], acc[ai][bj][m][n], 0, 0, 0); __builtin_amdgcn_s_setprio(0); } while (0)
; #define G8_WAIT_L(n) asm volatile("s_waitcnt lgkmcnt(" #n ")" ::: "memory")
; #define G8_BAR __builtin_amdgcn_s_barrier()
;     ...
;         const bool has_next = next_unit<NKH, ROT>(ui + 1, nM, nN, nxt);
;         const char* nA = uptr(has_next ? (const char*)A + (size_t)nxt.pm * tstepA + (size_t)nxt.kh * kchunk + E.a_off(nxt.pn) : cA);
;         const char* nB = uptr(has_next ? (const char*)Bt + (size_t)nxt.pn * tstepB + (size_t)nxt.kh * kchunk : cB);
;         for (int t = 0; t < nt; t += 2) {
;             const bool last = (t == nt - 2);
;             const char* a1 = cA + (size_t)(t + 1) * kstep;
;             const char* a2 = last ? nA : cA + (size_t)(t + 2) * kstep; const char* b2 = last ? nB : cB + (size_t)(t + 2) * kstep;
;             const char* a3 = a2 + kstep; const char* b3 = b2 + kstep;
;             G8_LDB(B0, 0, 0); G8_SCHED; G8_LDA(At, 0, 0); G8_STAGE(G8_SA(1, 1), a1 + hstepA, voffA);
;             G8_WAIT_L(8); G8_BAR; G8_WAIT_L(0); G8_MMA(0, 0, At, B0); G8_BAR; G8_SCHED;
;             G8_LDB(B1, 0, 1); G8_STAGE(G8_SB(0, 0), b2, voffB);
;             G8_BAR; G8_WAIT_L(0); G8_MMA(0, 1, At, B1); G8_BAR;
;             G8_LDA(At, 0, 1); G8_STAGE(G8_SA(0, 0), a2, voffA);
;             G8_BAR; G8_WAIT_L(0); G8_MMA(1, 0, At, B0); G8_BAR; G8_SCHED;
.LBB0_1170:
	s_ashr_i32 s11, s10, 31
	s_xor_b64 s[12:13], s[16:17], -1
	s_lshl_b64 s[14:15], s[10:11], 21
	s_add_u32 s9, s84, s14
	s_addc_u32 s11, s85, s15
	s_and_b64 s[14:15], s[16:17], exec
	s_cselect_b32 s14, s9, s2
	s_cselect_b32 s15, s11, s3
	s_ashr_i32 s9, s8, 31
	s_lshl_b64 s[24:25], s[8:9], 21
	s_add_u32 s9, s29, s24
	s_addc_u32 s11, s30, s25
	s_and_b64 s[16:17], s[16:17], exec
	s_cselect_b32 s16, s9, s22
	s_cselect_b32 s17, s11, s23
	s_add_u32 s9, s22, 0x100
	s_addc_u32 s11, s23, 0
	s_add_u32 s2, s2, 0x100080
	s_addc_u32 s3, s3, 0
	s_mov_b32 s19, -2
	ds_read_b128 v[112:115], v218
	ds_read_b128 v[120:123], v218 offset:1024
	ds_read_b128 v[136:139], v218 offset:2048
	ds_read_b128 v[140:143], v218 offset:3072
	s_add_u32 s21, s2, 0xfff00080
	s_addc_u32 s22, s3, -1
	s_cmp_eq_u32 s19, 60
	s_cselect_b32 s26, s14, s21
	s_cselect_b32 s27, s15, s22
	s_cselect_b32 s22, s16, s9
	s_cselect_b32 s23, s17, s11
	s_add_u32 s24, s26, 0x80
	s_addc_u32 s25, s27, 0
	v_lshl_add_u64 v[176:177], s[2:3], 0, v[184:185]
	s_add_i32 m0, s33, 0xc000
	ds_read_b128 v[144:147], v219
	ds_read_b128 v[148:151], v219 offset:1024
	ds_read_b128 v[152:155], v219 offset:2048
	ds_read_b128 v[156:159], v219 offset:3072
	ds_read_b128 v[160:163], v219 offset:4096
	ds_read_b128 v[164:167], v219 offset:5120
	ds_read_b128 v[168:171], v219 offset:6144
	ds_read_b128 v[172:175], v219 offset:7168
	global_load_lds_dwordx4 v[176:177], off
	v_lshl_add_u64 v[176:177], s[2:3], 0, v[188:189]
	s_add_i32 m0, s33, 0xe000
	s_nop 0
	global_load_lds_dwordx4 v[176:177], off
	s_waitcnt lgkmcnt(8)
	s_barrier
	s_waitcnt lgkmcnt(0)
	s_setprio 1
	s_waitcnt lgkmcnt(0)
	v_mfma_f32_16x16x32_bf16 v[132:135], v[112:115], v[144:147], 0
	v_mfma_f32_16x16x32_bf16 v[128:131], v[136:139], v[144:147], 0
	v_mfma_f32_16x16x32_bf16 v[108:111], v[112:115], v[152:155], 0
	v_mfma_f32_16x16x32_bf16 v[104:107], v[136:139], v[152:155], 0
	v_mfma_f32_16x16x32_bf16 v[92:95], v[112:115], v[160:163], 0
	v_mfma_f32_16x16x32_bf16 v[88:91], v[136:139], v[160:163], 0
	v_mfma_f32_16x16x32_bf16 v[76:79], v[112:115], v[168:171], 0
	v_mfma_f32_16x16x32_bf16 v[72:75], v[136:139], v[168:171], 0
	v_mfma_f32_16x16x32_bf16 v[132:135], v[120:123], v[148:151], v[132:135]
	v_mfma_f32_16x16x32_bf16 v[128:131], v[140:143], v[148:151], v[128:131]
	v_mfma_f32_16x16x32_bf16 v[108:111], v[120:123], v[156:159], v[108:111]
	v_mfma_f32_16x16x32_bf16 v[104:107], v[140:143], v[156:159], v[104:107]
	v_mfma_f32_16x16x32_bf16 v[92:95], v[120:123], v[164:167], v[92:95]
	v_mfma_f32_16x16x32_bf16 v[88:91], v[140:143], v[164:167], v[88:91]
	v_mfma_f32_16x16x32_bf16 v[76:79], v[120:123], v[172:175], v[76:79]
	v_mfma_f32_16x16x32_bf16 v[72:75], v[140:143], v[172:175], v[72:75]
	s_setprio 0
	s_barrier
	s_add_i32 s21, s44, s31
	v_lshl_add_u64 v[204:205], s[22:23], 0, v[186:187]
	s_mov_b32 m0, s21
	ds_read_b128 v[176:179], v220
	ds_read_b128 v[180:183], v220 offset:1024
	ds_read_b128 v[196:199], v220 offset:2048
	ds_read_b128 v[200:203], v220 offset:3072
	global_load_lds_dwordx4 v[204:205], off
	v_lshl_add_u64 v[204:205], s[22:23], 0, v[190:191]
	s_add_i32 m0, s21, 0x2000
	s_nop 0
	global_load_lds_dwordx4 v[204:205], off
	s_barrier
	s_waitcnt lgkmcnt(0)
	s_setprio 1
	s_waitcnt lgkmcnt(0)
	v_mfma_f32_16x16x32_bf16 v[124:127], v[176:179], v[144:147], 0
	v_mfma_f32_16x16x32_bf16 v[116:119], v[196:199], v[144:147], 0
	v_mfma_f32_16x16x32_bf16 v[100:103], v[176:179], v[152:155], 0
	v_mfma_f32_16x16x32_bf16 v[96:99], v[196:199], v[152:155], 0
	v_mfma_f32_16x16x32_bf16 v[84:87], v[176:179], v[160:163], 0
	v_mfma_f32_16x16x32_bf16 v[80:83], v[196:199], v[160:163], 0
	v_mfma_f32_16x16x32_bf16 v[68:71], v[176:179], v[168:171], 0
	v_mfma_f32_16x16x32_bf16 v[64:67], v[196:199], v[168:171], 0
	v_mfma_f32_16x16x32_bf16 v[124:127], v[180:183], v[148:151], v[124:127]
	v_mfma_f32_16x16x32_bf16 v[116:119], v[200:203], v[148:151], v[116:119]
	v_mfma_f32_16x16x32_bf16 v[100:103], v[180:183], v[156:159], v[100:103]
	v_mfma_f32_16x16x32_bf16 v[96:99], v[200:203], v[156:159], v[96:99]
	v_mfma_f32_16x16x32_bf16 v[84:87], v[180:183], v[164:167], v[84:87]
	v_mfma_f32_16x16x32_bf16 v[80:83], v[200:203], v[164:167], v[80:83]
	v_mfma_f32_16x16x32_bf16 v[68:71], v[180:183], v[172:175], v[68:71]
	v_mfma_f32_16x16x32_bf16 v[64:67], v[200:203], v[172:175], v[64:67]
	s_setprio 0
	s_mov_b32 m0, s33
	v_lshl_add_u64 v[204:205], s[26:27], 0, v[184:185]
	s_barrier
	ds_read_b128 v[144:147], v219 offset:16384
	ds_read_b128 v[148:151], v219 offset:17408
	ds_read_b128 v[152:155], v219 offset:18432
	ds_read_b128 v[156:159], v219 offset:19456
	ds_read_b128 v[160:163], v219 offset:20480
	ds_read_b128 v[164:167], v219 offset:21504
	ds_read_b128 v[168:171], v219 offset:22528
	ds_read_b128 v[172:175], v219 offset:23552
	global_load_lds_dwordx4 v[204:205], off
	v_lshl_add_u64 v[204:205], s[26:27], 0, v[188:189]
	s_mov_b32 m0, s34
	s_nop 0
	global_load_lds_dwordx4 v[204:205], off
	s_barrier
	s_waitcnt lgkmcnt(0)
	s_setprio 1
	s_waitcnt lgkmcnt(0)
	v_mfma_f32_16x16x32_bf16 v[60:63], v[112:115], v[144:147], 0
	v_mfma_f32_16x16x32_bf16 v[56:59], v[136:139], v[144:147], 0
	v_mfma_f32_16x16x32_bf16 v[44:47], v[112:115], v[152:155], 0
	v_mfma_f32_16x16x32_bf16 v[40:43], v[136:139], v[152:155], 0
	v_mfma_f32_16x16x32_bf16 v[28:31], v[112:115], v[160:163], 0
	v_mfma_f32_16x16x32_bf16 v[24:27], v[136:139], v[160:163], 0
	v_mfma_f32_16x16x32_bf16 v[12:15], v[112:115], v[168:171], 0
	v_mfma_f32_16x16x32_bf16 v[8:11], v[136:139], v[168:171], 0
	v_mfma_f32_16x16x32_bf16 v[60:63], v[120:123], v[148:151], v[60:63]
	v_mfma_f32_16x16x32_bf16 v[56:59], v[140:143], v[148:151], v[56:59]
	v_mfma_f32_16x16x32_bf16 v[44:47], v[120:123], v[156:159], v[44:47]
	v_mfma_f32_16x16x32_bf16 v[40:43], v[140:143], v[156:159], v[40:43]
	v_mfma_f32_16x16x32_bf16 v[28:31], v[120:123], v[164:167], v[28:31]
	v_mfma_f32_16x16x32_bf16 v[24:27], v[140:143], v[164:167], v[24:27]
	v_mfma_f32_16x16x32_bf16 v[12:15], v[120:123], v[172:175], v[12:15]
	v_mfma_f32_16x16x32_bf16 v[8:11], v[140:143], v[172:175], v[8:11]
	s_setprio 0
	s_barrier
; #define G8_STAGE(bufoff, gbase, voff) do { const char* _gb = uptr((const char*)(gbase)); _Pragma("unroll") for (int _i = 0; _i < 2; ++_i) \
;         __builtin_amdgcn_global_load_lds((const unsigned*)(_gb + (voff)[_i]), (LAS unsigned*)(lds + (bufoff) + ldsw + _i * 8192), 16, 0, 0); } while (0)
; #define G8_LDA(dst, b, h) do { _Pragma("unroll") for (int m = 0; m < 4; ++m) _Pragma("unroll") for (int k = 0; k < 2; ++k) dst[m][k] = *(const LAS bf16x8*)(lds + G8_SA(b, h) + aoff + m * 2048 + k * 1024); } while (0)
; #define G8_LDB(dst, b, h) do { _Pragma("unroll") for (int n = 0; n < 2; ++n) _Pragma("unroll") for (int k = 0; k < 2; ++k) dst[n][k] = *(const LAS bf16x8*)(lds + G8_SB(b, h) + boff + n * 2048 + k * 1024); } while (0)
; #define G8_MMA(ai, bj, At, Bt_) do { __builtin_amdgcn_s_setprio(1); _Pragma("unroll") for (int m = 0; m < 4; ++m) _Pragma("unroll") for (int n = 0; n < 2; ++n) _Pragma("unroll") for (int k = 0; k < 2; ++k) \
;         acc[ai][bj][m][n] = __builtin_amdgcn_mfma_f32_16x16x32_bf16(Bt_[n][k], At[m][k], acc[ai][bj][m][n], 0, 0, 0); __builtin_amdgcn_s_setprio(0); } while (0)
; #define G8_WAIT_V(n) asm volatile("s_waitcnt vmcnt(" #n ")" ::: "memory")
; #define G8_WAIT_L(n) asm volatile("s_waitcnt lgkmcnt(" #n ")" ::: "memory")
; #define G8_BAR __builtin_amdgcn_s_barrier()
; #define G8_SCHED __builtin_amdgcn_sched_barrier(0)
;     ...
;             G8_STAGE(G8_SB(0, 1), b2 + hstepB, voffB);
;             G8_WAIT_V(6); G8_BAR; G8_MMA(1, 1, At, B1); G8_BAR;
;             G8_LDB(B0, 1, 0); G8_SCHED; G8_LDA(At, 1, 0); G8_STAGE(G8_SA(0, 1), a2 + hstepA, voffA);
;             G8_WAIT_L(8); G8_BAR; G8_WAIT_L(0); G8_MMA(0, 0, At, B0); G8_BAR; G8_SCHED;
;             G8_LDB(B1, 1, 1); G8_STAGE(G8_SB(1, 0), b3, voffB);
;             G8_BAR; G8_WAIT_L(0); G8_MMA(0, 1, At, B1); G8_BAR;
;             G8_LDA(At, 1, 1); G8_STAGE(G8_SA(1, 0), a3, voffA);
	s_add_u32 s48, s22, 0x100000
	s_addc_u32 s49, s23, 0
	s_add_i32 s21, s45, s31
	v_lshl_add_u64 v[112:113], s[48:49], 0, v[186:187]
	s_mov_b32 m0, s21
	s_nop 0
	global_load_lds_dwordx4 v[112:113], off
	v_lshl_add_u64 v[112:113], s[48:49], 0, v[190:191]
	s_add_i32 m0, s21, 0x2000
	s_nop 0
	global_load_lds_dwordx4 v[112:113], off
	s_waitcnt vmcnt(6)
	s_barrier
	s_setprio 1
	v_mfma_f32_16x16x32_bf16 v[52:55], v[176:179], v[144:147], 0
	v_mfma_f32_16x16x32_bf16 v[48:51], v[196:199], v[144:147], 0
	v_mfma_f32_16x16x32_bf16 v[36:39], v[176:179], v[152:155], 0
	v_mfma_f32_16x16x32_bf16 v[32:35], v[196:199], v[152:155], 0
	v_mfma_f32_16x16x32_bf16 v[20:23], v[176:179], v[160:163], 0
	v_mfma_f32_16x16x32_bf16 v[16:19], v[196:199], v[160:163], 0
	v_mfma_f32_16x16x32_bf16 v[4:7], v[176:179], v[168:171], 0
	v_mfma_f32_16x16x32_bf16 v[0:3], v[196:199], v[168:171], 0
	v_mfma_f32_16x16x32_bf16 v[52:55], v[180:183], v[148:151], v[52:55]
	v_mfma_f32_16x16x32_bf16 v[48:51], v[200:203], v[148:151], v[48:51]
	v_mfma_f32_16x16x32_bf16 v[36:39], v[180:183], v[156:159], v[36:39]
	v_mfma_f32_16x16x32_bf16 v[32:35], v[200:203], v[156:159], v[32:35]
	v_mfma_f32_16x16x32_bf16 v[20:23], v[180:183], v[164:167], v[20:23]
	v_mfma_f32_16x16x32_bf16 v[16:19], v[200:203], v[164:167], v[16:19]
	v_mfma_f32_16x16x32_bf16 v[4:7], v[180:183], v[172:175], v[4:7]
	v_mfma_f32_16x16x32_bf16 v[0:3], v[200:203], v[172:175], v[0:3]
	s_setprio 0
	s_add_i32 s21, 0, 0x18000
	v_add_u32_e32 v140, s21, v217
	s_barrier
	ds_read_b128 v[112:115], v140
	ds_read_b128 v[120:123], v140 offset:1024
	ds_read_b128 v[136:139], v140 offset:2048
	ds_read_b128 v[140:143], v140 offset:3072
	s_add_u32 s26, s26, 0x100000
	s_addc_u32 s27, s27, 0
	s_mov_b32 m0, s35
	v_lshl_add_u64 v[176:177], s[26:27], 0, v[184:185]
	ds_read_b128 v[144:147], v219 offset:32768
	ds_read_b128 v[148:151], v219 offset:33792
	ds_read_b128 v[152:155], v219 offset:34816
	ds_read_b128 v[156:159], v219 offset:35840
	ds_read_b128 v[160:163], v219 offset:36864
	ds_read_b128 v[164:167], v219 offset:37888
	ds_read_b128 v[168:171], v219 offset:38912
	ds_read_b128 v[172:175], v219 offset:39936
	global_load_lds_dwordx4 v[176:177], off
	v_lshl_add_u64 v[176:177], s[26:27], 0, v[188:189]
	s_mov_b32 m0, s36
	s_nop 0
	global_load_lds_dwordx4 v[176:177], off
	s_waitcnt lgkmcnt(8)
	s_barrier
	s_waitcnt lgkmcnt(0)
	s_setprio 1
	s_waitcnt lgkmcnt(0)
	v_mfma_f32_16x16x32_bf16 v[132:135], v[112:115], v[144:147], v[132:135]
	v_mfma_f32_16x16x32_bf16 v[128:131], v[136:139], v[144:147], v[128:131]
	v_mfma_f32_16x16x32_bf16 v[108:111], v[112:115], v[152:155], v[108:111]
	v_mfma_f32_16x16x32_bf16 v[104:107], v[136:139], v[152:155], v[104:107]
	v_mfma_f32_16x16x32_bf16 v[92:95], v[112:115], v[160:163], v[92:95]
	v_mfma_f32_16x16x32_bf16 v[88:91], v[136:139], v[160:163], v[88:91]
	v_mfma_f32_16x16x32_bf16 v[76:79], v[112:115], v[168:171], v[76:79]
	v_mfma_f32_16x16x32_bf16 v[72:75], v[136:139], v[168:171], v[72:75]
	v_mfma_f32_16x16x32_bf16 v[132:135], v[120:123], v[148:151], v[132:135]
	v_mfma_f32_16x16x32_bf16 v[128:131], v[140:143], v[148:151], v[128:131]
	v_mfma_f32_16x16x32_bf16 v[108:111], v[120:123], v[156:159], v[108:111]
	v_mfma_f32_16x16x32_bf16 v[104:107], v[140:143], v[156:159], v[104:107]
	v_mfma_f32_16x16x32_bf16 v[92:95], v[120:123], v[164:167], v[92:95]
	v_mfma_f32_16x16x32_bf16 v[88:91], v[140:143], v[164:167], v[88:91]
	v_mfma_f32_16x16x32_bf16 v[76:79], v[120:123], v[172:175], v[76:79]
	v_mfma_f32_16x16x32_bf16 v[72:75], v[140:143], v[172:175], v[72:75]
	s_setprio 0
	s_barrier
	s_add_i32 s47, 0, 0x1c000
	s_add_u32 s26, s22, 0x80
	s_addc_u32 s27, s23, 0
	s_add_i32 s21, s21, s31
	v_add_u32_e32 v200, s47, v217
	v_lshl_add_u64 v[204:205], s[26:27], 0, v[186:187]
	s_mov_b32 m0, s21
	ds_read_b128 v[176:179], v200
	ds_read_b128 v[180:183], v200 offset:1024
	ds_read_b128 v[196:199], v200 offset:2048
	ds_read_b128 v[200:203], v200 offset:3072
	global_load_lds_dwordx4 v[204:205], off
	v_lshl_add_u64 v[204:205], s[26:27], 0, v[190:191]
	s_add_i32 m0, s21, 0x2000
	s_nop 0
	global_load_lds_dwordx4 v[204:205], off
	s_barrier
; #define G8_STAGE(bufoff, gbase, voff) do { const char* _gb = uptr((const char*)(gbase)); _Pragma("unroll") for (int _i = 0; _i < 2; ++_i) \
;         __builtin_amdgcn_global_load_lds((const unsigned*)(_gb + (voff)[_i]), (LAS unsigned*)(lds + (bufoff) + ldsw + _i * 8192), 16, 0, 0); } while (0)
; #define G8_LDA(dst, b, h) do { _Pragma("unroll") for (int m = 0; m < 4; ++m) _Pragma("unroll") for (int k = 0; k < 2; ++k) dst[m][k] = *(const LAS bf16x8*)(lds + G8_SA(b, h) + aoff + m * 2048 + k * 1024); } while (0)
; #define G8_MMA(ai, bj, At, Bt_) do { __builtin_amdgcn_s_setprio(1); _Pragma("unroll") for (int m = 0; m < 4; ++m) _Pragma("unroll") for (int n = 0; n < 2; ++n) _Pragma("unroll") for (int k = 0; k < 2; ++k) \
;         acc[ai][bj][m][n] = __builtin_amdgcn_mfma_f32_16x16x32_bf16(Bt_[n][k], At[m][k], acc[ai][bj][m][n], 0, 0, 0); __builtin_amdgcn_s_setprio(0); } while (0)
; #define G8_WAIT_V(n) asm volatile("s_waitcnt vmcnt(" #n ")" ::: "memory")
; #define G8_WAIT_L(n) asm volatile("s_waitcnt lgkmcnt(" #n ")" ::: "memory")
; #define G8_BAR __builtin_amdgcn_s_barrier()
; #define G8_SCHED __builtin_amdgcn_sched_barrier(0)
;     ...
;             G8_LDA(At, 1, 1); G8_STAGE(G8_SA(1, 0), a3, voffA);
;             G8_BAR; G8_WAIT_L(0); G8_MMA(1, 0, At, B0); G8_BAR; G8_SCHED;
;             G8_STAGE(G8_SB(1, 1), b3 + hstepB, voffB);
;             G8_WAIT_V(6); G8_BAR; G8_MMA(1, 1, At, B1); G8_BAR;
;         }
	s_waitcnt lgkmcnt(0)
	s_setprio 1
	s_waitcnt lgkmcnt(0)
	v_mfma_f32_16x16x32_bf16 v[124:127], v[176:179], v[144:147], v[124:127]
	v_mfma_f32_16x16x32_bf16 v[116:119], v[196:199], v[144:147], v[116:119]
	v_mfma_f32_16x16x32_bf16 v[100:103], v[176:179], v[152:155], v[100:103]
	v_mfma_f32_16x16x32_bf16 v[96:99], v[196:199], v[152:155], v[96:99]
	v_mfma_f32_16x16x32_bf16 v[84:87], v[176:179], v[160:163], v[84:87]
	v_mfma_f32_16x16x32_bf16 v[80:83], v[196:199], v[160:163], v[80:83]
	v_mfma_f32_16x16x32_bf16 v[68:71], v[176:179], v[168:171], v[68:71]
	v_mfma_f32_16x16x32_bf16 v[64:67], v[196:199], v[168:171], v[64:67]
	v_mfma_f32_16x16x32_bf16 v[124:127], v[180:183], v[148:151], v[124:127]
	v_mfma_f32_16x16x32_bf16 v[116:119], v[200:203], v[148:151], v[116:119]
	v_mfma_f32_16x16x32_bf16 v[100:103], v[180:183], v[156:159], v[100:103]
	v_mfma_f32_16x16x32_bf16 v[96:99], v[200:203], v[156:159], v[96:99]
	v_mfma_f32_16x16x32_bf16 v[84:87], v[180:183], v[164:167], v[84:87]
	v_mfma_f32_16x16x32_bf16 v[80:83], v[200:203], v[164:167], v[80:83]
	v_mfma_f32_16x16x32_bf16 v[68:71], v[180:183], v[172:175], v[68:71]
	v_mfma_f32_16x16x32_bf16 v[64:67], v[200:203], v[172:175], v[64:67]
	s_setprio 0
	s_mov_b32 m0, s39
	v_lshl_add_u64 v[204:205], s[24:25], 0, v[184:185]
	s_barrier
	ds_read_b128 v[144:147], v219 offset:49152
	ds_read_b128 v[148:151], v219 offset:50176
	ds_read_b128 v[152:155], v219 offset:51200
	ds_read_b128 v[156:159], v219 offset:52224
	ds_read_b128 v[160:163], v219 offset:53248
	ds_read_b128 v[164:167], v219 offset:54272
	ds_read_b128 v[168:171], v219 offset:55296
	ds_read_b128 v[172:175], v219 offset:56320
	global_load_lds_dwordx4 v[204:205], off
	v_lshl_add_u64 v[204:205], s[24:25], 0, v[188:189]
	s_mov_b32 m0, s40
	s_nop 0
	global_load_lds_dwordx4 v[204:205], off
	s_barrier
	s_waitcnt lgkmcnt(0)
	s_setprio 1
	s_waitcnt lgkmcnt(0)
	v_mfma_f32_16x16x32_bf16 v[60:63], v[112:115], v[144:147], v[60:63]
	v_mfma_f32_16x16x32_bf16 v[56:59], v[136:139], v[144:147], v[56:59]
	v_mfma_f32_16x16x32_bf16 v[44:47], v[112:115], v[152:155], v[44:47]
	v_mfma_f32_16x16x32_bf16 v[40:43], v[136:139], v[152:155], v[40:43]
	v_mfma_f32_16x16x32_bf16 v[28:31], v[112:115], v[160:163], v[28:31]
	v_mfma_f32_16x16x32_bf16 v[24:27], v[136:139], v[160:163], v[24:27]
	v_mfma_f32_16x16x32_bf16 v[12:15], v[112:115], v[168:171], v[12:15]
	v_mfma_f32_16x16x32_bf16 v[8:11], v[136:139], v[168:171], v[8:11]
	v_mfma_f32_16x16x32_bf16 v[60:63], v[120:123], v[148:151], v[60:63]
	v_mfma_f32_16x16x32_bf16 v[56:59], v[140:143], v[148:151], v[56:59]
	v_mfma_f32_16x16x32_bf16 v[44:47], v[120:123], v[156:159], v[44:47]
	v_mfma_f32_16x16x32_bf16 v[40:43], v[140:143], v[156:159], v[40:43]
	v_mfma_f32_16x16x32_bf16 v[28:31], v[120:123], v[164:167], v[28:31]
	v_mfma_f32_16x16x32_bf16 v[24:27], v[140:143], v[164:167], v[24:27]
	v_mfma_f32_16x16x32_bf16 v[12:15], v[120:123], v[172:175], v[12:15]
	v_mfma_f32_16x16x32_bf16 v[8:11], v[140:143], v[172:175], v[8:11]
	s_setprio 0
	s_barrier
	s_add_u32 s22, s22, 0x100080
	s_addc_u32 s23, s23, 0
	s_add_i32 s21, s47, s31
	v_lshl_add_u64 v[112:113], s[22:23], 0, v[186:187]
	s_mov_b32 m0, s21
	s_nop 0
	global_load_lds_dwordx4 v[112:113], off
	v_lshl_add_u64 v[112:113], s[22:23], 0, v[190:191]
	s_add_i32 m0, s21, 0x2000
	s_nop 0
	global_load_lds_dwordx4 v[112:113], off
	s_waitcnt vmcnt(6)
	s_barrier
	s_setprio 1
	v_mfma_f32_16x16x32_bf16 v[52:55], v[176:179], v[144:147], v[52:55]
	v_mfma_f32_16x16x32_bf16 v[48:51], v[196:199], v[144:147], v[48:51]
	v_mfma_f32_16x16x32_bf16 v[36:39], v[176:179], v[152:155], v[36:39]
	v_mfma_f32_16x16x32_bf16 v[32:35], v[196:199], v[152:155], v[32:35]
	v_mfma_f32_16x16x32_bf16 v[20:23], v[176:179], v[160:163], v[20:23]
	v_mfma_f32_16x16x32_bf16 v[16:19], v[196:199], v[160:163], v[16:19]
	v_mfma_f32_16x16x32_bf16 v[4:7], v[176:179], v[168:171], v[4:7]
	v_mfma_f32_16x16x32_bf16 v[0:3], v[196:199], v[168:171], v[0:3]
	v_mfma_f32_16x16x32_bf16 v[52:55], v[180:183], v[148:151], v[52:55]
	v_mfma_f32_16x16x32_bf16 v[48:51], v[200:203], v[148:151], v[48:51]
	v_mfma_f32_16x16x32_bf16 v[36:39], v[180:183], v[156:159], v[36:39]
	v_mfma_f32_16x16x32_bf16 v[32:35], v[200:203], v[156:159], v[32:35]
	v_mfma_f32_16x16x32_bf16 v[20:23], v[180:183], v[164:167], v[20:23]
	v_mfma_f32_16x16x32_bf16 v[16:19], v[200:203], v[164:167], v[16:19]
	v_mfma_f32_16x16x32_bf16 v[4:7], v[180:183], v[172:175], v[4:7]
	v_mfma_f32_16x16x32_bf16 v[0:3], v[200:203], v[172:175], v[0:3]
	s_setprio 0
	s_add_i32 s19, s19, 2
	s_add_u32 s9, s9, 0x100
	s_addc_u32 s11, s11, 0
	s_add_u32 s2, s2, 0x100
	s_addc_u32 s3, s3, 0
	s_cmp_gt_u32 s19, 61
	s_barrier
